# lists phase: second-pass items take the mirrored chunk so every wave has the same prefix-scan length
# baseline (speedup 1.0000x reference)
; __device__ __forceinline__ void lists_phase(const Args& a, int tid, int lane, int wave) {
;     ...
;     for (int wv = BID * NWAVES + wave; wv < Bn * 8 * (S / 64); wv += nwv) {
;         const int bh = __builtin_amdgcn_readfirstlane(wv / (S / 64)), w = __builtin_amdgcn_readfirstlane(wv % (S / 64));
;         const int t = w * 64 + lane, blk = w >> 2;
;         unsigned off = 0u;
;         { const unsigned* wc_ = WCNT + (size_t)bh * 128 * 32 + (lane & 31); unsigned o0 = 0u, o1 = 0u, o2 = 0u, o3 = 0u; int w2 = 0;
;           for (; w2 + 4 <= w; w2 += 4) { o0 += wc_[(w2 + 0) * 32]; o1 += wc_[(w2 + 1) * 32]; o2 += wc_[(w2 + 2) * 32]; o3 += wc_[(w2 + 3) * 32]; }
;           for (; w2 < w; ++w2) o0 += wc_[w2 * 32];
;           off = (o0 + o1) + (o2 + o3); }
.LBB0_636:
	s_ashr_i32 s6, s3, 31
	s_lshr_b32 s6, s6, 25
	s_add_i32 s6, s3, s6
	s_ashr_i32 s10, s6, 7
	s_and_b32 s6, s6, 0xffffff80
	s_ashr_i32 s11, s10, 31
	s_sub_i32 s19, s3, s6
	s_sub_i32 s98, 0x7f, s19
	s_cmpk_lt_i32 s3, 0x800
	s_cselect_b32 s19, s19, s98
	s_lshl_b64 s[12:13], s[10:11], 14
	s_add_u32 s12, s14, s12
	s_addc_u32 s13, s15, s13
	v_lshl_add_u64 v[8:9], s[12:13], 0, v[6:7]
	s_cmp_lt_i32 s19, 4
	v_mov_b32_e32 v10, 0
	v_mov_b32_e32 v12, 0
	v_mov_b32_e32 v11, 0
	s_mov_b32 s22, s7
	v_mov_b32_e32 v13, 0
	s_cbranch_scc1 .LBB0_644
	s_add_i32 s6, s19, -4
	s_mov_b32 s20, 4
	s_cmp_lt_u32 s6, 4
	v_readfirstlane_b32 s22, v0
	s_cbranch_scc1 .LBB0_641
	s_lshr_b32 s21, s6, 2
	s_add_i32 s21, s21, 1
	s_and_b32 s22, s21, 0x7ffffffe
	v_mov_b32_e32 v10, 0
	s_mov_b32 s23, 0
	s_mov_b32 s24, s22
	v_mov_b32_e32 v11, 0
	v_mov_b32_e32 v12, 0
	v_mov_b32_e32 v14, 0
	v_mov_b32_e32 v15, 0
	v_mov_b32_e32 v16, 0
	v_mov_b32_e32 v17, 0
	v_mov_b32_e32 v18, 0
